# OutA GEMM epilogue: 16 gate loads hoisted up front into dead fragment registers, counted vmcnt waits
# speedup vs baseline: 1.0755x; 1.0024x over previous
.LBB0_634:
	v_lshl_add_u32 v144, s42, 8, v146
	v_lshl_or_b32 v142, s41, 8, v148
	v_ashrrev_i32_e32 v145, 31, v144
	v_ashrrev_i32_e32 v143, 31, v142
	v_lshlrev_b64 v[140:141], 10, v[144:145]
	v_lshl_add_u64 v[140:141], v[140:141], 0, v[142:143]
	v_lshlrev_b64 v[140:141], 1, v[140:141]
	s_mov_b64 s[22:23], s[10:11]
	global_load_dwordx4 v[160:163], v140, s[22:23]
	global_load_dwordx4 v[164:167], v140, s[22:23] offset:256
	s_add_u32 s22, s10, 0x8000
	s_addc_u32 s23, s11, 0
	global_load_dwordx4 v[178:181], v140, s[22:23]
	global_load_dwordx4 v[182:185], v140, s[22:23] offset:256
	s_add_u32 s22, s10, 0x10000
	s_addc_u32 s23, s11, 0
	global_load_dwordx4 v[186:189], v140, s[22:23]
	global_load_dwordx4 v[190:193], v140, s[22:23] offset:256
	s_add_u32 s22, s10, 0x18000
	s_addc_u32 s23, s11, 0
	global_load_dwordx4 v[208:211], v140, s[22:23]
	global_load_dwordx4 v[212:215], v140, s[22:23] offset:256
	s_add_u32 s22, s10, 0x40000
	s_addc_u32 s23, s11, 0
	global_load_dwordx4 v[216:219], v140, s[22:23]
	global_load_dwordx4 v[220:223], v140, s[22:23] offset:256
	s_add_u32 s22, s10, 0x48000
	s_addc_u32 s23, s11, 0
	global_load_dwordx4 v[224:227], v140, s[22:23]
	global_load_dwordx4 v[228:231], v140, s[22:23] offset:256
	s_add_u32 s22, s10, 0x50000
	s_addc_u32 s23, s11, 0
	global_load_dwordx4 v[236:239], v140, s[22:23]
	global_load_dwordx4 v[240:243], v140, s[22:23] offset:256
	s_add_u32 s22, s10, 0x58000
	s_addc_u32 s23, s11, 0
	global_load_dwordx4 v[244:247], v140, s[22:23]
	global_load_dwordx4 v[248:251], v140, s[22:23] offset:256
	v_lshl_add_u64 v[154:155], s[10:11], 0, v[140:141]
	s_mov_b64 s[22:23], 0x40000
	s_andn2_b64 vcc, exec, s[4:5]
	s_waitcnt vmcnt(15)
	v_lshlrev_b32_e32 v156, 16, v160
	v_and_b32_e32 v157, 0xffff0000, v160
	v_lshlrev_b32_e32 v150, 16, v161
	v_and_b32_e32 v151, 0xffff0000, v161
	v_lshlrev_b32_e32 v158, 16, v162
	v_and_b32_e32 v159, 0xffff0000, v162
	v_lshlrev_b32_e32 v152, 16, v163
	v_and_b32_e32 v153, 0xffff0000, v163
	v_pk_mul_f32 v[126:127], v[126:127], v[150:151]
	v_pk_mul_f32 v[124:125], v[124:125], v[156:157]
	v_pk_mul_f32 v[150:151], v[122:123], v[152:153]
	v_pk_mul_f32 v[122:123], v[120:121], v[158:159]
	v_cvt_pk_bf16_f32 v120, v124, v125
	v_cvt_pk_bf16_f32 v121, v126, v127
	v_cvt_pk_bf16_f32 v122, v122, v123
	v_cvt_pk_bf16_f32 v123, v150, v151
	v_lshl_add_u64 v[124:125], s[8:9], 0, v[140:141]
	global_store_dwordx4 v[124:125], v[120:123], off
	s_waitcnt vmcnt(15)
	v_lshlrev_b32_e32 v126, 16, v164
	v_and_b32_e32 v127, 0xffff0000, v164
	v_lshlrev_b32_e32 v120, 16, v165
	v_and_b32_e32 v121, 0xffff0000, v165
	v_lshlrev_b32_e32 v150, 16, v166
	v_and_b32_e32 v151, 0xffff0000, v166
	v_lshlrev_b32_e32 v122, 16, v167
	v_and_b32_e32 v123, 0xffff0000, v167
	v_pk_mul_f32 v[118:119], v[118:119], v[120:121]
	v_pk_mul_f32 v[116:117], v[116:117], v[126:127]
	v_pk_mul_f32 v[120:121], v[114:115], v[122:123]
	v_pk_mul_f32 v[114:115], v[112:113], v[150:151]
	v_cvt_pk_bf16_f32 v112, v116, v117
	v_cvt_pk_bf16_f32 v113, v118, v119
	v_cvt_pk_bf16_f32 v114, v114, v115
	v_cvt_pk_bf16_f32 v115, v120, v121
	global_store_dwordx4 v[124:125], v[112:115], off offset:256
	s_nop 1
	v_or_b32_e32 v112, 16, v144
	v_ashrrev_i32_e32 v113, 31, v112
	v_lshlrev_b64 v[112:113], 10, v[112:113]
	v_lshl_add_u64 v[112:113], v[112:113], 0, v[142:143]
	v_lshlrev_b64 v[116:117], 1, v[112:113]
	v_lshl_add_u64 v[118:119], s[10:11], 0, v[116:117]
	s_waitcnt vmcnt(15)
	v_lshlrev_b32_e32 v120, 16, v178
	v_and_b32_e32 v121, 0xffff0000, v178
	v_lshlrev_b32_e32 v112, 16, v179
	v_and_b32_e32 v113, 0xffff0000, v179
	v_lshlrev_b32_e32 v122, 16, v180
	v_and_b32_e32 v123, 0xffff0000, v180
	v_lshlrev_b32_e32 v114, 16, v181
	v_and_b32_e32 v115, 0xffff0000, v181
	v_pk_mul_f32 v[110:111], v[110:111], v[112:113]
	v_pk_mul_f32 v[108:109], v[108:109], v[120:121]
	v_pk_mul_f32 v[112:113], v[106:107], v[114:115]
	v_pk_mul_f32 v[106:107], v[104:105], v[122:123]
	v_cvt_pk_bf16_f32 v104, v108, v109
	v_cvt_pk_bf16_f32 v105, v110, v111
	v_cvt_pk_bf16_f32 v106, v106, v107
	v_cvt_pk_bf16_f32 v107, v112, v113
	v_lshl_add_u64 v[108:109], s[8:9], 0, v[116:117]
	global_store_dwordx4 v[108:109], v[104:107], off
	s_waitcnt vmcnt(15)
	v_lshlrev_b32_e32 v110, 16, v182
	v_and_b32_e32 v111, 0xffff0000, v182
	v_lshlrev_b32_e32 v104, 16, v183
	v_and_b32_e32 v105, 0xffff0000, v183
	v_lshlrev_b32_e32 v112, 16, v184
	v_and_b32_e32 v113, 0xffff0000, v184
	v_lshlrev_b32_e32 v106, 16, v185
	v_and_b32_e32 v107, 0xffff0000, v185
	v_pk_mul_f32 v[102:103], v[102:103], v[104:105]
	v_pk_mul_f32 v[100:101], v[100:101], v[110:111]
	v_pk_mul_f32 v[104:105], v[98:99], v[106:107]
	v_pk_mul_f32 v[98:99], v[96:97], v[112:113]
	v_cvt_pk_bf16_f32 v96, v100, v101
	v_cvt_pk_bf16_f32 v97, v102, v103
	v_cvt_pk_bf16_f32 v98, v98, v99
	v_cvt_pk_bf16_f32 v99, v104, v105
	global_store_dwordx4 v[108:109], v[96:99], off offset:256
	s_nop 1
	v_or_b32_e32 v96, 32, v144
	v_ashrrev_i32_e32 v97, 31, v96
	v_lshlrev_b64 v[96:97], 10, v[96:97]
	v_lshl_add_u64 v[96:97], v[96:97], 0, v[142:143]
	v_lshlrev_b64 v[100:101], 1, v[96:97]
	v_lshl_add_u64 v[102:103], s[10:11], 0, v[100:101]
	s_waitcnt vmcnt(15)
	v_lshlrev_b32_e32 v104, 16, v186
	v_and_b32_e32 v105, 0xffff0000, v186
	v_lshlrev_b32_e32 v96, 16, v187
	v_and_b32_e32 v97, 0xffff0000, v187
	v_lshlrev_b32_e32 v106, 16, v188
	v_and_b32_e32 v107, 0xffff0000, v188
	v_lshlrev_b32_e32 v98, 16, v189
	v_and_b32_e32 v99, 0xffff0000, v189
	v_pk_mul_f32 v[94:95], v[94:95], v[96:97]
	v_pk_mul_f32 v[92:93], v[92:93], v[104:105]
	v_pk_mul_f32 v[96:97], v[90:91], v[98:99]
	v_pk_mul_f32 v[90:91], v[88:89], v[106:107]
	v_cvt_pk_bf16_f32 v88, v92, v93
	v_cvt_pk_bf16_f32 v89, v94, v95
	v_cvt_pk_bf16_f32 v90, v90, v91
	v_cvt_pk_bf16_f32 v91, v96, v97
	v_lshl_add_u64 v[92:93], s[8:9], 0, v[100:101]
	global_store_dwordx4 v[92:93], v[88:91], off
	s_waitcnt vmcnt(15)
	v_lshlrev_b32_e32 v94, 16, v190
	v_and_b32_e32 v95, 0xffff0000, v190
	v_lshlrev_b32_e32 v88, 16, v191
	v_and_b32_e32 v89, 0xffff0000, v191
	v_lshlrev_b32_e32 v96, 16, v192
	v_and_b32_e32 v97, 0xffff0000, v192
	v_lshlrev_b32_e32 v90, 16, v193
	v_and_b32_e32 v91, 0xffff0000, v193
	v_pk_mul_f32 v[86:87], v[86:87], v[88:89]
	v_pk_mul_f32 v[84:85], v[84:85], v[94:95]
	v_pk_mul_f32 v[88:89], v[82:83], v[90:91]
	v_pk_mul_f32 v[82:83], v[80:81], v[96:97]
	v_cvt_pk_bf16_f32 v80, v84, v85
	v_cvt_pk_bf16_f32 v81, v86, v87
	v_cvt_pk_bf16_f32 v82, v82, v83
	v_cvt_pk_bf16_f32 v83, v88, v89
	global_store_dwordx4 v[92:93], v[80:83], off offset:256
	s_nop 1
	v_or_b32_e32 v80, 48, v144
	v_ashrrev_i32_e32 v81, 31, v80
	v_lshlrev_b64 v[80:81], 10, v[80:81]
	v_lshl_add_u64 v[80:81], v[80:81], 0, v[142:143]
	v_lshlrev_b64 v[84:85], 1, v[80:81]
	v_lshl_add_u64 v[86:87], s[10:11], 0, v[84:85]
	s_waitcnt vmcnt(15)
	v_lshlrev_b32_e32 v88, 16, v208
	v_and_b32_e32 v89, 0xffff0000, v208
	v_lshlrev_b32_e32 v80, 16, v209
	v_and_b32_e32 v81, 0xffff0000, v209
	v_lshlrev_b32_e32 v90, 16, v210
	v_and_b32_e32 v91, 0xffff0000, v210
	v_lshlrev_b32_e32 v82, 16, v211
	v_and_b32_e32 v83, 0xffff0000, v211
	v_pk_mul_f32 v[78:79], v[78:79], v[80:81]
	v_pk_mul_f32 v[76:77], v[76:77], v[88:89]
	v_pk_mul_f32 v[80:81], v[74:75], v[82:83]
	v_pk_mul_f32 v[74:75], v[72:73], v[90:91]
	v_cvt_pk_bf16_f32 v72, v76, v77
	v_cvt_pk_bf16_f32 v73, v78, v79
	v_cvt_pk_bf16_f32 v74, v74, v75
	v_cvt_pk_bf16_f32 v75, v80, v81
	v_lshl_add_u64 v[76:77], s[8:9], 0, v[84:85]
	global_store_dwordx4 v[76:77], v[72:75], off
	s_waitcnt vmcnt(15)
	v_lshlrev_b32_e32 v78, 16, v212
	v_and_b32_e32 v79, 0xffff0000, v212
	v_lshlrev_b32_e32 v72, 16, v213
	v_and_b32_e32 v73, 0xffff0000, v213
	v_lshlrev_b32_e32 v80, 16, v214
	v_and_b32_e32 v81, 0xffff0000, v214
	v_lshlrev_b32_e32 v74, 16, v215
	v_and_b32_e32 v75, 0xffff0000, v215
	v_pk_mul_f32 v[70:71], v[70:71], v[72:73]
	v_pk_mul_f32 v[68:69], v[68:69], v[78:79]
	v_pk_mul_f32 v[72:73], v[66:67], v[74:75]
	v_pk_mul_f32 v[66:67], v[64:65], v[80:81]
	v_cvt_pk_bf16_f32 v64, v68, v69
	v_cvt_pk_bf16_f32 v65, v70, v71
	v_cvt_pk_bf16_f32 v66, v66, v67
	v_cvt_pk_bf16_f32 v67, v72, v73
	global_store_dwordx4 v[76:77], v[64:67], off offset:256
	v_lshl_add_u64 v[68:69], v[140:141], 0, s[22:23]
	v_lshl_add_u64 v[70:71], s[10:11], 0, v[68:69]
	s_mov_b64 s[22:23], 0x48000
	s_waitcnt vmcnt(15)
	v_lshlrev_b32_e32 v72, 16, v216
	v_and_b32_e32 v73, 0xffff0000, v216
	v_lshlrev_b32_e32 v64, 16, v217
	v_and_b32_e32 v65, 0xffff0000, v217
	v_lshlrev_b32_e32 v74, 16, v218
	v_and_b32_e32 v75, 0xffff0000, v218
	v_lshlrev_b32_e32 v66, 16, v219
	v_and_b32_e32 v67, 0xffff0000, v219
	v_pk_mul_f32 v[62:63], v[62:63], v[64:65]
	v_pk_mul_f32 v[60:61], v[60:61], v[72:73]
	v_pk_mul_f32 v[64:65], v[58:59], v[66:67]
	v_pk_mul_f32 v[58:59], v[56:57], v[74:75]
	v_cvt_pk_bf16_f32 v56, v60, v61
	v_cvt_pk_bf16_f32 v57, v62, v63
	v_cvt_pk_bf16_f32 v58, v58, v59
	v_cvt_pk_bf16_f32 v59, v64, v65
	v_lshl_add_u64 v[60:61], s[8:9], 0, v[68:69]
	global_store_dwordx4 v[60:61], v[56:59], off
	s_waitcnt vmcnt(15)
	v_lshlrev_b32_e32 v62, 16, v220
	v_and_b32_e32 v63, 0xffff0000, v220
	v_lshlrev_b32_e32 v56, 16, v221
	v_and_b32_e32 v57, 0xffff0000, v221
	v_lshlrev_b32_e32 v64, 16, v222
	v_and_b32_e32 v65, 0xffff0000, v222
	v_lshlrev_b32_e32 v58, 16, v223
	v_and_b32_e32 v59, 0xffff0000, v223
	v_pk_mul_f32 v[54:55], v[54:55], v[56:57]
	v_pk_mul_f32 v[52:53], v[52:53], v[62:63]
	v_pk_mul_f32 v[56:57], v[50:51], v[58:59]
	v_pk_mul_f32 v[50:51], v[48:49], v[64:65]
	v_cvt_pk_bf16_f32 v48, v52, v53
	v_cvt_pk_bf16_f32 v49, v54, v55
	v_cvt_pk_bf16_f32 v50, v50, v51
	v_cvt_pk_bf16_f32 v51, v56, v57
	global_store_dwordx4 v[60:61], v[48:51], off offset:256
	v_lshl_add_u64 v[52:53], v[140:141], 0, s[22:23]
	v_lshl_add_u64 v[54:55], s[10:11], 0, v[52:53]
	s_mov_b64 s[22:23], 0x50000
	s_waitcnt vmcnt(15)
	v_lshlrev_b32_e32 v56, 16, v224
	v_and_b32_e32 v57, 0xffff0000, v224
	v_lshlrev_b32_e32 v48, 16, v225
	v_and_b32_e32 v49, 0xffff0000, v225
	v_lshlrev_b32_e32 v58, 16, v226
	v_and_b32_e32 v59, 0xffff0000, v226
	v_lshlrev_b32_e32 v50, 16, v227
	v_and_b32_e32 v51, 0xffff0000, v227
	v_pk_mul_f32 v[46:47], v[46:47], v[48:49]
	v_pk_mul_f32 v[44:45], v[44:45], v[56:57]
	v_pk_mul_f32 v[48:49], v[42:43], v[50:51]
	v_pk_mul_f32 v[42:43], v[40:41], v[58:59]
	v_cvt_pk_bf16_f32 v40, v44, v45
	v_cvt_pk_bf16_f32 v41, v46, v47
	v_cvt_pk_bf16_f32 v42, v42, v43
	v_cvt_pk_bf16_f32 v43, v48, v49
	v_lshl_add_u64 v[44:45], s[8:9], 0, v[52:53]
	global_store_dwordx4 v[44:45], v[40:43], off
	s_waitcnt vmcnt(15)
	v_lshlrev_b32_e32 v46, 16, v228
	v_and_b32_e32 v47, 0xffff0000, v228
	v_lshlrev_b32_e32 v40, 16, v229
	v_and_b32_e32 v41, 0xffff0000, v229
	v_lshlrev_b32_e32 v48, 16, v230
	v_and_b32_e32 v49, 0xffff0000, v230
	v_lshlrev_b32_e32 v42, 16, v231
	v_and_b32_e32 v43, 0xffff0000, v231
	v_pk_mul_f32 v[38:39], v[38:39], v[40:41]
	v_pk_mul_f32 v[36:37], v[36:37], v[46:47]
	v_pk_mul_f32 v[40:41], v[34:35], v[42:43]
	v_pk_mul_f32 v[34:35], v[32:33], v[48:49]
	v_cvt_pk_bf16_f32 v32, v36, v37
	v_cvt_pk_bf16_f32 v33, v38, v39
	v_cvt_pk_bf16_f32 v34, v34, v35
	v_cvt_pk_bf16_f32 v35, v40, v41
	global_store_dwordx4 v[44:45], v[32:35], off offset:256
	v_lshl_add_u64 v[36:37], v[140:141], 0, s[22:23]
	v_lshl_add_u64 v[38:39], s[10:11], 0, v[36:37]
	s_mov_b64 s[22:23], 0x58000
	s_waitcnt vmcnt(15)
	v_lshlrev_b32_e32 v40, 16, v236
	v_and_b32_e32 v41, 0xffff0000, v236
	v_lshlrev_b32_e32 v32, 16, v237
	v_and_b32_e32 v33, 0xffff0000, v237
	v_lshlrev_b32_e32 v42, 16, v238
	v_and_b32_e32 v43, 0xffff0000, v238
	v_lshlrev_b32_e32 v34, 16, v239
	v_and_b32_e32 v35, 0xffff0000, v239
	v_pk_mul_f32 v[30:31], v[30:31], v[32:33]
	v_pk_mul_f32 v[28:29], v[28:29], v[40:41]
	v_pk_mul_f32 v[32:33], v[26:27], v[34:35]
	v_pk_mul_f32 v[26:27], v[24:25], v[42:43]
	v_cvt_pk_bf16_f32 v24, v28, v29
	v_cvt_pk_bf16_f32 v25, v30, v31
	v_cvt_pk_bf16_f32 v26, v26, v27
	v_cvt_pk_bf16_f32 v27, v32, v33
	v_lshl_add_u64 v[28:29], s[8:9], 0, v[36:37]
	global_store_dwordx4 v[28:29], v[24:27], off
	s_waitcnt vmcnt(15)
	v_lshlrev_b32_e32 v30, 16, v240
	v_and_b32_e32 v31, 0xffff0000, v240
	v_lshlrev_b32_e32 v24, 16, v241
	v_and_b32_e32 v25, 0xffff0000, v241
	v_lshlrev_b32_e32 v32, 16, v242
	v_and_b32_e32 v33, 0xffff0000, v242
	v_lshlrev_b32_e32 v26, 16, v243
	v_and_b32_e32 v27, 0xffff0000, v243
	v_pk_mul_f32 v[22:23], v[22:23], v[24:25]
	v_pk_mul_f32 v[20:21], v[20:21], v[30:31]
	v_pk_mul_f32 v[24:25], v[18:19], v[26:27]
	v_pk_mul_f32 v[18:19], v[16:17], v[32:33]
	v_cvt_pk_bf16_f32 v16, v20, v21
	v_cvt_pk_bf16_f32 v17, v22, v23
	v_cvt_pk_bf16_f32 v18, v18, v19
	v_cvt_pk_bf16_f32 v19, v24, v25
	global_store_dwordx4 v[28:29], v[16:19], off offset:256
	v_lshl_add_u64 v[20:21], v[140:141], 0, s[22:23]
	v_lshl_add_u64 v[22:23], s[10:11], 0, v[20:21]
	s_mov_b64 s[22:23], -1
	s_waitcnt vmcnt(15)
	v_lshlrev_b32_e32 v24, 16, v244
	v_and_b32_e32 v25, 0xffff0000, v244
	v_lshlrev_b32_e32 v16, 16, v245
	v_and_b32_e32 v17, 0xffff0000, v245
	v_lshlrev_b32_e32 v26, 16, v246
	v_and_b32_e32 v27, 0xffff0000, v246
	v_lshlrev_b32_e32 v18, 16, v247
	v_and_b32_e32 v19, 0xffff0000, v247
	v_pk_mul_f32 v[14:15], v[14:15], v[16:17]
	v_pk_mul_f32 v[12:13], v[12:13], v[24:25]
	v_pk_mul_f32 v[16:17], v[10:11], v[18:19]
	v_pk_mul_f32 v[10:11], v[8:9], v[26:27]
	v_cvt_pk_bf16_f32 v8, v12, v13
	v_cvt_pk_bf16_f32 v9, v14, v15
	v_cvt_pk_bf16_f32 v10, v10, v11
	v_cvt_pk_bf16_f32 v11, v16, v17
	v_lshl_add_u64 v[12:13], s[8:9], 0, v[20:21]
	global_store_dwordx4 v[12:13], v[8:11], off
	s_waitcnt vmcnt(15)
	v_lshlrev_b32_e32 v14, 16, v248
	v_and_b32_e32 v15, 0xffff0000, v248
	v_lshlrev_b32_e32 v8, 16, v249
	v_and_b32_e32 v9, 0xffff0000, v249
	v_lshlrev_b32_e32 v16, 16, v250
	v_and_b32_e32 v17, 0xffff0000, v250
	v_lshlrev_b32_e32 v10, 16, v251
	v_and_b32_e32 v11, 0xffff0000, v251
	v_pk_mul_f32 v[6:7], v[6:7], v[8:9]
	v_pk_mul_f32 v[4:5], v[4:5], v[14:15]
	v_pk_mul_f32 v[8:9], v[2:3], v[10:11]
	v_pk_mul_f32 v[2:3], v[0:1], v[16:17]
	v_cvt_pk_bf16_f32 v0, v4, v5
	v_cvt_pk_bf16_f32 v1, v6, v7
	v_cvt_pk_bf16_f32 v2, v2, v3
	v_cvt_pk_bf16_f32 v3, v8, v9
	global_store_dwordx4 v[12:13], v[0:3], off offset:256
	s_cbranch_vccnz .LBB0_623
	s_andn2_b64 vcc, exec, s[2:3]
	s_cbranch_vccnz .LBB0_622
	s_barrier
	s_branch .LBB0_622
